# P2 prompt chunk P*V phase: V^T LDS fragment reads double-buffered (two register quads) and issued one step ahead behind the consuming MFMA; 16 exposed lgkmcnt(0) round trips removed
# baseline (speedup 1.0000x reference)
.LBB0_728:
	s_or_b64 exec, exec, s[12:13]
	v_readfirstlane_b32 s14, v0
	s_cmp_ge_i32 s14, s22
	s_mov_b64 s[12:13], -1
	s_cbranch_scc1 .LBB0_723
	s_cmp_ge_i32 s14, s21
	v_lshlrev_b32_e32 v92, 1, v138
	v_mbcnt_hi_u32_b32 v102, -1, v220
	s_cbranch_scc0 .LBB0_731
	s_sub_i32 s12, s14, s21
	s_and_b32 s15, s12, 3
	s_lshl_b32 s13, s15, 5
	v_or_b32_e32 v0, s13, v154
	s_lshr_b32 s12, s12, 2
	v_ashrrev_i32_e32 v1, 31, v0
	v_readlane_b32 s24, v254, 54
	v_lshlrev_b64 v[84:85], 12, v[0:1]
	v_readlane_b32 s25, v254, 55
	s_add_i32 s12, s12, s23
	v_mov_b32_e32 v93, v131
	v_lshl_add_u64 v[0:1], s[24:25], 0, v[84:85]
	s_lshl_b32 s24, s12, 7
	s_mov_b32 s25, s92
	v_lshl_add_u64 v[0:1], v[0:1], 0, s[24:25]
	v_lshl_add_u64 v[90:91], v[0:1], 0, v[92:93]
	global_load_dwordx4 v[68:71], v[90:91], off
	global_load_dwordx4 v[64:67], v[90:91], off offset:32
	s_add_i32 s93, s15, 1
	v_lshl_or_b32 v4, s93, 5, v136
	v_mad_u32_u24 v94, v4, s16, v129
	ds_read_b128 v[16:19], v94
	ds_read_b128 v[76:79], v94 offset:32
	s_add_i32 s94, s15, 2
	v_lshl_or_b32 v20, s94, 5, v136
	v_mad_u32_u24 v95, v20, s16, v129
	v_or_b32_e32 v2, s13, v136
	s_add_i32 s95, s15, 3
	v_mad_u32_u24 v93, v2, s16, v129
	v_lshl_or_b32 v20, s95, 5, v136
	ds_read_b128 v[0:3], v93
	ds_read_b128 v[72:75], v93 offset:32
	v_mad_u32_u24 v96, v20, s16, v129
	s_mov_b32 s13, s92
	v_readlane_b32 s56, v254, 22
	s_or_b32 s24, s15, 4
	s_lshl_b64 vcc, s[12:13], 2
	v_readlane_b32 s58, v254, 24
	v_readlane_b32 s59, v254, 25
	s_add_u32 vcc_lo, s58, vcc_lo
	s_addc_u32 vcc_hi, s59, vcc_hi
	s_cmp_eq_u32 s15, 3
	v_readlane_b32 s57, v254, 23
	v_readlane_b32 s56, v255, 4
	v_readlane_b32 s57, v255, 5
	v_readlane_b32 s60, v254, 26
	v_readlane_b32 s61, v254, 27
	v_readlane_b32 s62, v254, 28
	v_readlane_b32 s63, v254, 29
	v_readlane_b32 s64, v254, 30
	v_readlane_b32 s65, v254, 31
	v_readlane_b32 s66, v254, 32
	v_readlane_b32 s67, v254, 33
	v_readlane_b32 s68, v254, 34
	v_readlane_b32 s69, v254, 35
	v_readlane_b32 s70, v254, 36
	v_readlane_b32 s71, v254, 37
	s_waitcnt vmcnt(1) lgkmcnt(3)
	v_mfma_f32_32x32x16_bf16 v[48:63], v[16:19], v[68:71], 0
	ds_read_b128 v[16:19], v95
	ds_read_b128 v[80:83], v95 offset:32
	s_waitcnt lgkmcnt(1)
	v_mfma_f32_32x32x16_bf16 v[32:47], v[16:19], v[68:71], 0
	ds_read_b128 v[16:19], v96
	ds_read_b128 v[86:89], v96 offset:32
	s_waitcnt vmcnt(0)
	v_mfma_f32_32x32x16_bf16 v[48:63], v[76:79], v[64:67], v[48:63]
	global_load_dwordx4 v[76:79], v[90:91], off offset:64
	v_mfma_f32_32x32x16_bf16 v[0:15], v[0:3], v[68:71], 0
	v_mfma_f32_32x32x16_bf16 v[0:15], v[72:75], v[64:67], v[0:15]
	global_load_dwordx4 v[72:75], v[90:91], off offset:96
	s_waitcnt lgkmcnt(1)
	v_mfma_f32_32x32x16_bf16 v[16:31], v[16:19], v[68:71], 0
	v_mfma_f32_32x32x16_bf16 v[32:47], v[80:83], v[64:67], v[32:47]
	s_waitcnt lgkmcnt(0)
	v_mfma_f32_32x32x16_bf16 v[16:31], v[86:89], v[64:67], v[16:31]
	ds_read_b128 v[86:89], v93 offset:64
	ds_read_b128 v[80:83], v93 offset:96
	s_waitcnt vmcnt(1) lgkmcnt(1)
	v_mfma_f32_32x32x16_bf16 v[0:15], v[86:89], v[76:79], v[0:15]
	ds_read_b128 v[86:89], v94 offset:64
	ds_read_b128 v[98:101], v94 offset:96
	s_waitcnt lgkmcnt(1)
	v_mfma_f32_32x32x16_bf16 v[48:63], v[86:89], v[76:79], v[48:63]
	ds_read_b128 v[86:89], v95 offset:64
	ds_read_b128 v[104:107], v95 offset:96
	s_waitcnt lgkmcnt(1)
	v_mfma_f32_32x32x16_bf16 v[32:47], v[86:89], v[76:79], v[32:47]
	ds_read_b128 v[86:89], v96 offset:64
	ds_read_b128 v[112:115], v96 offset:96
	global_load_dword v96, v131, vcc
	s_mov_b32 s62, 0x6e80000
	s_mov_b32 s63, 0
	s_mov_b32 s64, 0x4c80000
	s_mov_b32 s65, 0
	s_mov_b32 s66, 0x2a80000
	s_mov_b32 s67, 0
	v_lshl_add_u64 v[190:191], v[90:91], 0, s[62:63]
	global_load_dwordx4 v[222:225], v[190:191], off
	global_load_dwordx4 v[226:229], v[190:191], off offset:32
	global_load_dwordx4 v[230:233], v[190:191], off offset:64
	global_load_dwordx4 v[234:237], v[190:191], off offset:96
	v_lshl_add_u64 v[190:191], v[90:91], 0, s[64:65]
	global_load_dwordx4 v[238:241], v[190:191], off
	global_load_dwordx4 v[242:245], v[190:191], off offset:32
	global_load_dwordx4 v[246:249], v[190:191], off offset:64
	global_load_dwordx4 v[250:253], v[190:191], off offset:96
	v_lshl_add_u64 v[190:191], v[90:91], 0, s[66:67]
	global_load_dwordx4 v[182:185], v[190:191], off
	global_load_dwordx4 v[186:189], v[190:191], off offset:32
	global_load_dwordx4 v[202:205], v[190:191], off offset:64
	global_load_dwordx4 v[206:209], v[190:191], off offset:96
	s_mov_b32 s66, 0x2a7e000
	s_mov_b32 s70, 3
	s_mov_b32 s71, 3
	s_mov_b64 s[68:69], exec
	v_lshl_add_u64 v[190:191], v[90:91], 0, s[66:67]
	s_mov_b64 exec, s[70:71]
	global_load_dwordx4 v[144:147], v[190:191], off
	global_load_dwordx4 v[148:151], v[190:191], off offset:32
	global_load_dwordx4 v[192:195], v[190:191], off offset:64
	global_load_dwordx4 v[196:199], v[190:191], off offset:96
	s_mov_b64 exec, s[68:69]
	s_cselect_b64 vcc, -1, 0
	s_or_b64 vcc, s[8:9], vcc
	s_xor_b32 s13, s15, 2
	s_cmp_lt_u32 s13, 2
	s_waitcnt lgkmcnt(1)
	v_mfma_f32_32x32x16_bf16 v[16:31], v[86:89], v[76:79], v[16:31]
	s_waitcnt vmcnt(17)
	v_mfma_f32_32x32x16_bf16 v[48:63], v[98:101], v[72:75], v[48:63]
	v_mfma_f32_32x32x16_bf16 v[32:47], v[104:107], v[72:75], v[32:47]
	s_nop 10
	v_cndmask_b32_e32 v48, v179, v48, vcc
	v_cndmask_b32_e32 v49, v179, v49, vcc
	v_cndmask_b32_e32 v50, v179, v50, vcc
	v_cndmask_b32_e32 v51, v179, v51, vcc
	v_cndmask_b32_e32 v52, v179, v52, vcc
	v_cndmask_b32_e32 v53, v179, v53, vcc
	v_cndmask_b32_e32 v54, v179, v54, vcc
	s_waitcnt lgkmcnt(0)
	v_mfma_f32_32x32x16_bf16 v[16:31], v[112:115], v[72:75], v[16:31]
	v_cndmask_b32_e32 v55, v179, v55, vcc
	v_cndmask_b32_e32 v56, v179, v56, vcc
	v_cndmask_b32_e32 v57, v179, v57, vcc
	v_cndmask_b32_e32 v58, v179, v58, vcc
	v_cndmask_b32_e32 v59, v179, v59, vcc
	v_cndmask_b32_e32 v60, v179, v60, vcc
	v_cndmask_b32_e32 v61, v179, v61, vcc
	v_cndmask_b32_e32 v62, v179, v62, vcc
	v_cndmask_b32_e32 v116, v179, v63, vcc
	s_cselect_b64 vcc, -1, 0
	s_or_b64 vcc, s[8:9], vcc
	s_or_b32 s13, s15, s20
	s_cmp_eq_u32 s13, 0
	v_cndmask_b32_e32 v117, v179, v32, vcc
	v_cndmask_b32_e32 v118, v179, v33, vcc
	v_cndmask_b32_e32 v119, v179, v34, vcc
	v_cndmask_b32_e32 v120, v179, v35, vcc
	v_cndmask_b32_e32 v121, v179, v36, vcc
	v_cndmask_b32_e32 v122, v179, v37, vcc
	v_cndmask_b32_e32 v123, v179, v38, vcc
	v_cndmask_b32_e32 v130, v179, v39, vcc
	v_cndmask_b32_e32 v63, v179, v40, vcc
	v_cndmask_b32_e32 v111, v179, v41, vcc
	v_cndmask_b32_e32 v110, v179, v42, vcc
	v_cndmask_b32_e32 v109, v179, v43, vcc
	v_cndmask_b32_e32 v108, v179, v44, vcc
	v_cndmask_b32_e32 v107, v179, v45, vcc
	v_cndmask_b32_e32 v106, v179, v46, vcc
	v_cndmask_b32_e32 v105, v179, v47, vcc
	s_cselect_b64 vcc, -1, 0
	v_cndmask_b32_e32 v103, v17, v179, vcc
	v_and_b32_e32 v17, 64, v102
	v_cndmask_b32_e32 v104, v16, v179, vcc
	v_xor_b32_e32 v16, 32, v102
	v_add_u32_e32 v17, 64, v17
	v_cndmask_b32_e32 v101, v18, v179, vcc
	v_cndmask_b32_e32 v100, v19, v179, vcc
	v_cndmask_b32_e32 v99, v20, v179, vcc
	v_cndmask_b32_e32 v98, v21, v179, vcc
	v_cndmask_b32_e32 v97, v22, v179, vcc
	v_cndmask_b32_e32 v95, v23, v179, vcc
	v_cndmask_b32_e32 v94, v24, v179, vcc
	v_cndmask_b32_e32 v93, v25, v179, vcc
	v_cndmask_b32_e32 v91, v26, v179, vcc
	v_cndmask_b32_e32 v90, v27, v179, vcc
	v_cndmask_b32_e32 v86, v28, v179, vcc
	v_cndmask_b32_e32 v87, v29, v179, vcc
	v_cndmask_b32_e32 v88, v30, v179, vcc
	v_cndmask_b32_e32 v89, v31, v179, vcc
	v_cmp_lt_i32_e32 vcc, v16, v17
	v_mfma_f32_32x32x16_bf16 v[0:15], v[80:83], v[72:75], v[0:15]
	s_mov_b32 s13, 0x3fb8aa3b
	v_cndmask_b32_e32 v44, v102, v16, vcc
	v_lshl_or_b32 v16, s24, 5, v136
	v_mad_u32_u24 v40, v16, s16, v129
	ds_read_b128 v[16:19], v40
	ds_read_b128 v[32:35], v40 offset:32
	ds_read_b128 v[36:39], v40 offset:64
	ds_read_b128 v[40:43], v40 offset:96
	v_lshlrev_b32_e32 v112, 2, v44
	s_waitcnt lgkmcnt(3)
	v_mfma_f32_32x32x16_bf16 v[16:31], v[16:19], v[68:71], 0
	s_nop 0
	v_cndmask_b32_e64 v0, v179, v0, s[26:27]
	v_cndmask_b32_e64 v1, v179, v1, s[28:29]
	v_max3_f32 v45, v0, s17, v1
	v_cndmask_b32_e64 v2, v179, v2, s[30:31]
	v_cndmask_b32_e64 v3, v179, v3, s[34:35]
	v_cndmask_b32_e64 v4, v179, v4, s[36:37]
	v_cndmask_b32_e64 v5, v179, v5, s[38:39]
	s_waitcnt lgkmcnt(2)
	v_mfma_f32_32x32x16_bf16 v[16:31], v[32:35], v[64:67], v[16:31]
	v_max3_f32 v32, v45, v2, v3
	v_max3_f32 v32, v32, v4, v5
	v_cndmask_b32_e64 v6, v179, v6, s[96:97]
	v_cndmask_b32_e64 v7, v179, v7, s[2:3]
	v_max3_f32 v32, v32, v6, v7
	v_cndmask_b32_e64 v8, v179, v8, s[72:73]
	v_cndmask_b32_e64 v9, v179, v9, s[74:75]
	s_waitcnt lgkmcnt(1)
	v_mfma_f32_32x32x16_bf16 v[16:31], v[36:39], v[76:79], v[16:31]
	v_max3_f32 v32, v32, v8, v9
	v_cndmask_b32_e64 v34, v179, v10, s[76:77]
	v_cndmask_b32_e64 v11, v179, v11, s[78:79]
	v_max3_f32 v10, v32, v34, v11
	v_cndmask_b32_e64 v12, v179, v12, s[80:81]
	v_cndmask_b32_e64 v13, v179, v13, s[82:83]
	v_max3_f32 v10, v10, v12, v13
	s_waitcnt lgkmcnt(0)
	v_mfma_f32_32x32x16_bf16 v[16:31], v[40:43], v[72:75], v[16:31]
	v_cndmask_b32_e64 v14, v179, v14, s[84:85]
	v_cndmask_b32_e64 v15, v179, v15, s[86:87]
	v_max3_f32 v10, v10, v14, v15
	v_max3_f32 v10, v10, v48, v49
	v_max3_f32 v10, v10, v50, v51
	v_max3_f32 v10, v10, v52, v53
	v_max3_f32 v10, v10, v54, v55
	s_nop 4
	v_cndmask_b32_e64 v16, v16, v179, s[56:57]
	v_readlane_b32 s56, v255, 34
	v_readlane_b32 s57, v255, 35
	v_max3_f32 v10, v10, v56, v57
	v_max3_f32 v10, v10, v58, v59
	v_cndmask_b32_e64 v17, v179, v17, s[56:57]
	v_readlane_b32 s56, v255, 8
	v_readlane_b32 s57, v255, 9
	v_max3_f32 v10, v10, v60, v61
	v_max3_f32 v10, v10, v62, v116
	v_cndmask_b32_e64 v18, v18, v179, s[56:57]
	v_readlane_b32 s56, v255, 10
	v_readlane_b32 s57, v255, 11
	v_max3_f32 v10, v10, v117, v118
	v_max3_f32 v10, v10, v119, v120
	v_cndmask_b32_e64 v19, v19, v179, s[56:57]
	v_readlane_b32 s56, v255, 12
	v_readlane_b32 s57, v255, 13
	v_max3_f32 v10, v10, v121, v122
	v_max3_f32 v10, v10, v123, v130
	v_cndmask_b32_e64 v20, v20, v179, s[56:57]
	v_readlane_b32 s56, v255, 14
	v_readlane_b32 s57, v255, 15
	v_max3_f32 v10, v10, v63, v111
	v_max3_f32 v10, v10, v110, v109
	v_cndmask_b32_e64 v21, v21, v179, s[56:57]
	v_readlane_b32 s56, v255, 16
	v_readlane_b32 s57, v255, 17
	v_max3_f32 v10, v10, v108, v107
	v_max3_f32 v10, v10, v106, v105
	v_cndmask_b32_e64 v22, v22, v179, s[56:57]
	v_readlane_b32 s56, v255, 18
	v_readlane_b32 s57, v255, 19
	v_max3_f32 v10, v10, v104, v103
	v_max3_f32 v10, v10, v101, v100
	v_cndmask_b32_e64 v23, v23, v179, s[56:57]
	v_readlane_b32 s56, v255, 20
	v_readlane_b32 s57, v255, 21
	v_max3_f32 v10, v10, v99, v98
	v_max3_f32 v10, v10, v97, v95
	v_cndmask_b32_e64 v24, v24, v179, s[56:57]
	v_readlane_b32 s56, v255, 22
	v_readlane_b32 s57, v255, 23
	v_max3_f32 v10, v10, v94, v93
	v_max3_f32 v10, v10, v91, v90
	v_cndmask_b32_e64 v25, v25, v179, s[56:57]
	v_readlane_b32 s56, v255, 24
	v_readlane_b32 s57, v255, 25
	v_max3_f32 v10, v10, v86, v87
	v_max3_f32 v10, v10, v88, v89
	v_cndmask_b32_e64 v26, v26, v179, s[56:57]
	v_readlane_b32 s56, v255, 26
	v_readlane_b32 s57, v255, 27
	v_max3_f32 v10, v10, v16, v17
	v_max3_f32 v10, v10, v18, v19
	v_cndmask_b32_e64 v27, v27, v179, s[56:57]
	v_readlane_b32 s56, v255, 28
	v_readlane_b32 s57, v255, 29
	v_max3_f32 v10, v10, v20, v21
	v_max3_f32 v10, v10, v22, v23
	v_cndmask_b32_e64 v28, v28, v179, s[56:57]
	v_readlane_b32 s56, v255, 30
	v_readlane_b32 s57, v255, 31
	v_max3_f32 v10, v10, v24, v25
	v_max3_f32 v10, v10, v26, v27
	v_cndmask_b32_e64 v29, v29, v179, s[56:57]
	v_readlane_b32 s56, v255, 32
	v_readlane_b32 s57, v255, 33
	v_max3_f32 v10, v10, v28, v29
	s_waitcnt vmcnt(16)
	v_mul_f32_e32 v33, 0x3fb8aa3b, v96
	v_cndmask_b32_e64 v30, v30, v179, s[56:57]
	v_readlane_b32 s56, v255, 2
	v_readlane_b32 s57, v255, 3
	v_lshl_add_u32 v115, s93, 6, v139
	v_lshl_or_b32 v114, s12, 6, v137
	v_cndmask_b32_e64 v31, v31, v179, s[56:57]
	v_max3_f32 v10, v10, v30, v31
	ds_bpermute_b32 v32, v112, v10
	s_waitcnt lgkmcnt(0)
	v_max_f32_e32 v32, v32, v32
	v_max_f32_e32 v10, v10, v32
	v_mul_f32_e32 v10, 0x3e38aa3b, v10
	v_max_f32_e32 v10, v10, v33
	v_fma_f32 v0, v0, s18, -v10
	v_exp_f32_e32 v0, v0
	v_fma_f32 v1, v1, s18, -v10
	v_exp_f32_e32 v1, v1
	v_fma_f32 v2, v2, s18, -v10
	v_exp_f32_e32 v2, v2
	v_fma_f32 v3, v3, s18, -v10
	v_exp_f32_e32 v3, v3
	v_fma_f32 v4, v4, s18, -v10
	v_add_f32_e32 v32, 0, v0
	v_exp_f32_e32 v4, v4
	v_fma_f32 v5, v5, s18, -v10
	v_add_f32_e32 v32, v1, v32
	v_exp_f32_e32 v5, v5
	v_fma_f32 v6, v6, s18, -v10
	v_add_f32_e32 v32, v2, v32
	v_exp_f32_e32 v6, v6
	v_fma_f32 v7, v7, s18, -v10
	v_add_f32_e32 v32, v3, v32
	v_exp_f32_e32 v7, v7
	v_add_f32_e32 v32, v4, v32
	v_add_f32_e32 v32, v5, v32
	v_add_f32_e32 v32, v6, v32
	v_fma_f32 v8, v8, s18, -v10
	v_add_f32_e32 v36, v7, v32
	v_exp_f32_e32 v32, v8
	v_fma_f32 v8, v9, s18, -v10
	v_exp_f32_e32 v33, v8
	v_fma_f32 v8, v34, s18, -v10
	v_exp_f32_e32 v34, v8
	v_fma_f32 v8, v11, s18, -v10
	v_exp_f32_e32 v35, v8
	v_fma_f32 v9, v12, s18, -v10
	v_add_f32_e32 v8, v32, v36
	v_exp_f32_e32 v36, v9
	v_fma_f32 v9, v13, s18, -v10
	v_add_f32_e32 v8, v33, v8
	v_exp_f32_e32 v37, v9
	v_fma_f32 v9, v14, s18, -v10
	v_add_f32_e32 v8, v34, v8
	v_exp_f32_e32 v38, v9
	v_fma_f32 v9, v15, s18, -v10
	v_add_f32_e32 v8, v35, v8
	v_exp_f32_e32 v40, v9
	v_fma_f32 v9, v48, s18, -v10
	v_add_f32_e32 v8, v36, v8
	v_exp_f32_e32 v39, v9
	v_fma_f32 v9, v49, s18, -v10
	v_add_f32_e32 v8, v37, v8
	v_exp_f32_e32 v41, v9
	v_fma_f32 v9, v50, s18, -v10
	v_add_f32_e32 v8, v38, v8
	v_exp_f32_e32 v42, v9
	v_fma_f32 v9, v51, s18, -v10
	v_add_f32_e32 v8, v40, v8
	v_exp_f32_e32 v43, v9
	v_fma_f32 v9, v52, s18, -v10
	v_add_f32_e32 v8, v39, v8
	v_exp_f32_e32 v44, v9
	v_fma_f32 v9, v53, s18, -v10
	v_add_f32_e32 v8, v41, v8
	v_exp_f32_e32 v45, v9
	v_fma_f32 v9, v54, s18, -v10
	v_add_f32_e32 v8, v42, v8
	v_exp_f32_e32 v46, v9
	v_fma_f32 v9, v55, s18, -v10
	v_add_f32_e32 v8, v43, v8
	v_exp_f32_e32 v48, v9
	v_fma_f32 v9, v56, s18, -v10
	v_add_f32_e32 v8, v44, v8
	v_exp_f32_e32 v47, v9
	v_fma_f32 v9, v57, s18, -v10
	v_add_f32_e32 v8, v45, v8
	v_exp_f32_e32 v49, v9
	v_fma_f32 v9, v58, s18, -v10
	v_add_f32_e32 v8, v46, v8
	v_exp_f32_e32 v50, v9
	v_fma_f32 v9, v59, s18, -v10
	v_add_f32_e32 v8, v48, v8
	v_exp_f32_e32 v51, v9
	v_fma_f32 v9, v60, s18, -v10
	v_add_f32_e32 v8, v47, v8
	v_exp_f32_e32 v52, v9
	v_fma_f32 v9, v61, s18, -v10
	v_add_f32_e32 v8, v49, v8
	v_exp_f32_e32 v53, v9
	v_fma_f32 v9, v62, s18, -v10
	v_add_f32_e32 v8, v50, v8
	v_exp_f32_e32 v54, v9
	v_fma_f32 v9, v116, s18, -v10
	v_add_f32_e32 v8, v51, v8
	v_exp_f32_e32 v56, v9
	v_fma_f32 v9, v117, s18, -v10
	v_add_f32_e32 v8, v52, v8
	v_exp_f32_e32 v55, v9
	v_fma_f32 v9, v118, s18, -v10
	v_add_f32_e32 v8, v53, v8
	v_exp_f32_e32 v57, v9
	v_fma_f32 v9, v119, s18, -v10
	v_add_f32_e32 v8, v54, v8
	v_exp_f32_e32 v58, v9
	v_fma_f32 v9, v120, s18, -v10
	v_add_f32_e32 v8, v56, v8
	v_exp_f32_e32 v59, v9
	v_fma_f32 v9, v121, s18, -v10
	v_add_f32_e32 v8, v55, v8
	v_exp_f32_e32 v60, v9
	v_fma_f32 v9, v122, s18, -v10
	v_add_f32_e32 v8, v57, v8
	v_exp_f32_e32 v61, v9
	v_fma_f32 v9, v123, s18, -v10
	v_add_f32_e32 v8, v58, v8
	v_exp_f32_e32 v62, v9
	v_fma_f32 v9, v130, s18, -v10
	v_add_f32_e32 v8, v59, v8
	v_exp_f32_e32 v64, v9
	v_fma_f32 v9, v63, s18, -v10
	v_add_f32_e32 v8, v60, v8
	v_exp_f32_e32 v63, v9
	v_fma_f32 v9, v111, s18, -v10
	v_add_f32_e32 v8, v61, v8
	v_exp_f32_e32 v65, v9
	v_fma_f32 v9, v110, s18, -v10
	v_add_f32_e32 v8, v62, v8
	v_exp_f32_e32 v66, v9
	v_fma_f32 v9, v109, s18, -v10
	v_add_f32_e32 v8, v64, v8
	v_exp_f32_e32 v67, v9
	v_fma_f32 v9, v108, s18, -v10
	v_add_f32_e32 v8, v63, v8
	v_exp_f32_e32 v68, v9
	v_fma_f32 v9, v107, s18, -v10
	v_add_f32_e32 v8, v65, v8
	v_exp_f32_e32 v69, v9
	v_fma_f32 v9, v106, s18, -v10
	v_add_f32_e32 v8, v66, v8
	v_exp_f32_e32 v70, v9
	v_fma_f32 v9, v105, s18, -v10
	v_add_f32_e32 v8, v67, v8
	v_exp_f32_e32 v72, v9
	v_fma_f32 v9, v104, s18, -v10
	v_add_f32_e32 v8, v68, v8
	v_exp_f32_e32 v71, v9
	v_fma_f32 v9, v103, s18, -v10
	v_add_f32_e32 v8, v69, v8
	v_exp_f32_e32 v73, v9
	v_fma_f32 v9, v101, s18, -v10
	v_add_f32_e32 v8, v70, v8
	v_exp_f32_e32 v74, v9
	v_fma_f32 v9, v100, s18, -v10
	v_add_f32_e32 v8, v72, v8
	v_exp_f32_e32 v75, v9
	v_fma_f32 v9, v99, s18, -v10
	v_add_f32_e32 v8, v71, v8
	v_exp_f32_e32 v76, v9
	v_fma_f32 v9, v98, s18, -v10
	v_add_f32_e32 v8, v73, v8
	v_exp_f32_e32 v77, v9
	v_fma_f32 v9, v97, s18, -v10
	v_add_f32_e32 v8, v74, v8
	v_exp_f32_e32 v78, v9
	v_fma_f32 v9, v95, s18, -v10
	v_add_f32_e32 v8, v75, v8
	v_exp_f32_e32 v80, v9
	v_fma_f32 v9, v94, s18, -v10
	v_add_f32_e32 v8, v76, v8
	v_exp_f32_e32 v79, v9
	v_fma_f32 v9, v93, s18, -v10
	v_add_f32_e32 v8, v77, v8
	v_exp_f32_e32 v81, v9
	v_fma_f32 v9, v91, s18, -v10
	v_add_f32_e32 v8, v78, v8
	v_exp_f32_e32 v82, v9
	v_fma_f32 v9, v90, s18, -v10
	v_add_f32_e32 v8, v80, v8
	v_exp_f32_e32 v83, v9
	v_fma_f32 v9, v86, s18, -v10
	v_add_f32_e32 v8, v79, v8
	v_exp_f32_e32 v86, v9
	v_fma_f32 v9, v87, s18, -v10
	v_add_f32_e32 v8, v81, v8
	v_exp_f32_e32 v87, v9
	v_fma_f32 v9, v88, s18, -v10
	v_add_f32_e32 v8, v82, v8
	v_exp_f32_e32 v88, v9
	v_fma_f32 v9, v89, s18, -v10
	v_add_f32_e32 v8, v83, v8
	v_exp_f32_e32 v90, v9
	v_fma_f32 v9, v16, s18, -v10
	v_add_f32_e32 v8, v86, v8
	v_exp_f32_e32 v89, v9
	v_fma_f32 v9, v17, s18, -v10
	v_add_f32_e32 v8, v87, v8
	v_exp_f32_e32 v91, v9
	v_fma_f32 v9, v18, s18, -v10
	v_add_f32_e32 v8, v88, v8
	v_exp_f32_e32 v93, v9
	v_fma_f32 v9, v19, s18, -v10
	v_add_f32_e32 v8, v90, v8
	v_exp_f32_e32 v94, v9
	v_fma_f32 v9, v20, s18, -v10
	v_add_f32_e32 v8, v89, v8
	v_exp_f32_e32 v95, v9
	v_fma_f32 v9, v21, s18, -v10
	v_add_f32_e32 v8, v91, v8
	v_exp_f32_e32 v97, v9
	v_fma_f32 v9, v22, s18, -v10
	v_add_f32_e32 v8, v93, v8
	v_exp_f32_e32 v98, v9
	v_fma_f32 v9, v23, s18, -v10
	v_add_f32_e32 v8, v94, v8
	v_exp_f32_e32 v100, v9
	v_fma_f32 v9, v24, s18, -v10
	v_add_f32_e32 v8, v95, v8
	v_exp_f32_e32 v99, v9
	v_fma_f32 v9, v25, s18, -v10
	v_add_f32_e32 v8, v97, v8
	v_exp_f32_e32 v101, v9
	v_fma_f32 v9, v26, s18, -v10
	v_add_f32_e32 v8, v98, v8
	v_exp_f32_e32 v103, v9
	v_fma_f32 v9, v27, s18, -v10
	v_add_f32_e32 v8, v100, v8
	v_exp_f32_e32 v104, v9
	v_fma_f32 v9, v28, s18, -v10
	v_add_f32_e32 v8, v99, v8
	v_exp_f32_e32 v105, v9
	v_fma_f32 v9, v29, s18, -v10
	v_add_f32_e32 v8, v101, v8
	v_exp_f32_e32 v106, v9
	v_fma_f32 v9, v30, s18, -v10
	v_add_f32_e32 v8, v103, v8
	v_exp_f32_e32 v107, v9
	v_fma_f32 v9, v31, s18, -v10
	v_add_f32_e32 v8, v104, v8
	v_exp_f32_e32 v108, v9
	v_add_f32_e32 v8, v105, v8
	v_add_f32_e32 v8, v106, v8
	v_add_f32_e32 v8, v107, v8
	v_add_f32_e32 v8, v108, v8
	ds_bpermute_b32 v9, v112, v8
	v_fma_f32 v10, v96, s13, -v10
	v_exp_f32_e32 v10, v10
	v_cvt_pk_bf16_f32 v0, v0, v1
	v_cvt_pk_bf16_f32 v1, v2, v3
	s_waitcnt lgkmcnt(0)
	v_add_f32_e32 v8, v8, v9
	v_add_f32_e32 v96, v10, v8
	v_div_scale_f32 v8, vcc, v96, v96, 1.0
	v_rcp_f32_e32 v9, v8
	v_cvt_pk_bf16_f32 v2, v4, v5
	v_cvt_pk_bf16_f32 v3, v6, v7
	v_cvt_pk_bf16_f32 v32, v32, v33
	v_fma_f32 v10, -v8, v9, 1.0
	v_fmac_f32_e32 v9, v10, v9
	v_div_scale_f32 v10, vcc, 1.0, v96, 1.0
	v_mul_f32_e32 v11, v10, v9
	v_fma_f32 v12, -v8, v11, v10
	v_fmac_f32_e32 v11, v12, v9
	v_fma_f32 v8, -v8, v11, v10
	v_lshl_add_u32 v12, s15, 6, v139
	v_div_fmas_f32 v109, v8, v9, v11
	v_add_u32_e32 v8, v12, v157
	v_add_u32_e32 v110, 0x9000, v8
	ds_read2_b64 v[8:11], v110 offset1:2
	v_add_u32_e32 v4, v12, v158
	v_add_u32_e32 v119, 0x9000, v4
	ds_read2_b64 v[110:113], v110 offset0:4 offset1:6
	s_waitcnt lgkmcnt(1)
	v_mfma_f32_32x32x16_bf16 v[16:31], v[8:11], v[0:3], 0
	ds_read2_b64 v[4:7], v119 offset1:2
	v_cvt_pk_bf16_f32 v33, v34, v35
	v_cvt_pk_bf16_f32 v34, v36, v37
	v_cvt_pk_bf16_f32 v35, v38, v40
	v_cvt_pk_bf16_f32 v36, v39, v41
	v_cvt_pk_bf16_f32 v37, v42, v43
	v_cvt_pk_bf16_f32 v38, v44, v45
	s_waitcnt lgkmcnt(1)
	v_mfma_f32_32x32x16_bf16 v[16:31], v[110:113], v[32:35], v[16:31]
	ds_read2_b64 v[110:113], v119 offset0:4 offset1:6
	v_cvt_pk_bf16_f32 v39, v46, v48
	v_lshl_add_u32 v116, s94, 6, v139
	v_lshl_add_u32 v117, s95, 6, v139
	v_lshl_add_u32 v118, s24, 6, v139
	v_readlane_b32 s12, v254, 52
	v_readlane_b32 s13, v254, 53
	s_waitcnt lgkmcnt(1)
	v_mfma_f32_32x32x16_bf16 v[0:15], v[4:7], v[0:3], 0
	v_lshlrev_b32_e32 v130, 1, v114
	s_waitcnt lgkmcnt(0)
	v_mfma_f32_32x32x16_bf16 v[0:15], v[110:113], v[32:35], v[0:15]
	v_add_u32_e32 v42, v115, v157
	v_add_u32_e32 v40, 0x9000, v42
	v_add_u32_e32 v42, v115, v158
	v_add_u32_e32 v41, 0x9000, v42
	ds_read2_b64 v[32:35], v40 offset1:2
	ds_read2_b64 v[120:123], v41 offset1:2
	s_waitcnt lgkmcnt(1)
	s_nop 0
	v_mfma_f32_32x32x16_bf16 v[16:31], v[32:35], v[36:39], v[16:31]
	ds_read2_b64 v[32:35], v40 offset0:4 offset1:6
	s_waitcnt lgkmcnt(1)
	v_mfma_f32_32x32x16_bf16 v[0:15], v[120:123], v[36:39], v[0:15]
	ds_read2_b64 v[120:123], v41 offset0:4 offset1:6
	v_cvt_pk_bf16_f32 v36, v47, v49
	v_cvt_pk_bf16_f32 v37, v50, v51
	v_cvt_pk_bf16_f32 v38, v52, v53
	v_cvt_pk_bf16_f32 v39, v54, v56
	s_waitcnt lgkmcnt(1)
	s_nop 0
	v_mfma_f32_32x32x16_bf16 v[16:31], v[32:35], v[36:39], v[16:31]
	v_add_u32_e32 v42, v116, v157
	v_add_u32_e32 v40, 0x9000, v42
	ds_read2_b64 v[32:35], v40 offset1:2
	s_waitcnt lgkmcnt(1)
	v_mfma_f32_32x32x16_bf16 v[0:15], v[120:123], v[36:39], v[0:15]
	v_add_u32_e32 v42, v116, v158
	v_add_u32_e32 v41, 0x9000, v42
	ds_read2_b64 v[120:123], v41 offset1:2
	v_cvt_pk_bf16_f32 v36, v55, v57
	v_cvt_pk_bf16_f32 v37, v58, v59
	v_cvt_pk_bf16_f32 v38, v60, v61
	v_cvt_pk_bf16_f32 v39, v62, v64
	s_waitcnt lgkmcnt(1)
	s_nop 0
	v_mfma_f32_32x32x16_bf16 v[16:31], v[32:35], v[36:39], v[16:31]
	ds_read2_b64 v[32:35], v40 offset0:4 offset1:6
	s_waitcnt lgkmcnt(1)
	v_mfma_f32_32x32x16_bf16 v[0:15], v[120:123], v[36:39], v[0:15]
	ds_read2_b64 v[120:123], v41 offset0:4 offset1:6
	v_cvt_pk_bf16_f32 v36, v63, v65
	v_cvt_pk_bf16_f32 v37, v66, v67
	v_cvt_pk_bf16_f32 v38, v68, v69
	v_cvt_pk_bf16_f32 v39, v70, v72
	s_waitcnt lgkmcnt(1)
	s_nop 0
	v_mfma_f32_32x32x16_bf16 v[16:31], v[32:35], v[36:39], v[16:31]
	v_add_u32_e32 v42, v117, v157
	v_add_u32_e32 v40, 0x9000, v42
	ds_read2_b64 v[32:35], v40 offset1:2
	s_waitcnt lgkmcnt(1)
	v_mfma_f32_32x32x16_bf16 v[0:15], v[120:123], v[36:39], v[0:15]
	v_add_u32_e32 v42, v117, v158
	v_add_u32_e32 v41, 0x9000, v42
	ds_read2_b64 v[120:123], v41 offset1:2
	v_cvt_pk_bf16_f32 v36, v71, v73
	v_cvt_pk_bf16_f32 v37, v74, v75
	v_cvt_pk_bf16_f32 v38, v76, v77
	v_cvt_pk_bf16_f32 v39, v78, v80
	s_waitcnt lgkmcnt(1)
	s_nop 0
	v_mfma_f32_32x32x16_bf16 v[16:31], v[32:35], v[36:39], v[16:31]
	ds_read2_b64 v[32:35], v40 offset0:4 offset1:6
	s_waitcnt lgkmcnt(1)
	v_mfma_f32_32x32x16_bf16 v[0:15], v[120:123], v[36:39], v[0:15]
	ds_read2_b64 v[120:123], v41 offset0:4 offset1:6
	v_cvt_pk_bf16_f32 v36, v79, v81
	v_cvt_pk_bf16_f32 v37, v82, v83
	v_cvt_pk_bf16_f32 v38, v86, v87
	v_cvt_pk_bf16_f32 v39, v88, v90
	s_waitcnt lgkmcnt(1)
	s_nop 0
	v_mfma_f32_32x32x16_bf16 v[16:31], v[32:35], v[36:39], v[16:31]
	v_add_u32_e32 v42, v118, v157
	v_add_u32_e32 v40, 0x9000, v42
	ds_read2_b64 v[32:35], v40 offset1:2
	s_waitcnt lgkmcnt(1)
	v_mfma_f32_32x32x16_bf16 v[0:15], v[120:123], v[36:39], v[0:15]
	v_add_u32_e32 v42, v118, v158
	v_add_u32_e32 v41, 0x9000, v42
	ds_read2_b64 v[120:123], v41 offset1:2
	v_cvt_pk_bf16_f32 v36, v89, v91
	v_cvt_pk_bf16_f32 v37, v93, v94
	v_cvt_pk_bf16_f32 v38, v95, v97
	v_cvt_pk_bf16_f32 v39, v98, v100
	s_waitcnt lgkmcnt(1)
	s_nop 0
	v_mfma_f32_32x32x16_bf16 v[16:31], v[32:35], v[36:39], v[16:31]
	ds_read2_b64 v[32:35], v40 offset0:4 offset1:6
	s_waitcnt lgkmcnt(1)
	v_mfma_f32_32x32x16_bf16 v[0:15], v[120:123], v[36:39], v[0:15]
	ds_read2_b64 v[120:123], v41 offset0:4 offset1:6
	v_cvt_pk_bf16_f32 v36, v99, v101
	v_cvt_pk_bf16_f32 v37, v103, v104
	v_cvt_pk_bf16_f32 v38, v105, v106
	v_cvt_pk_bf16_f32 v39, v107, v108
	s_waitcnt lgkmcnt(1)
	s_nop 0
	v_mfma_f32_32x32x16_bf16 v[16:31], v[32:35], v[36:39], v[16:31]
	s_waitcnt lgkmcnt(0)
	v_mfma_f32_32x32x16_bf16 v[0:15], v[120:123], v[36:39], v[0:15]


	v_div_fixup_f32 v32, v109, v96, 1.0
	v_lshl_add_u64 v[34:35], s[12:13], 0, v[84:85]
	s_nop 6
	v_pk_mul_f32 v[16:17], v[16:17], v[32:33] op_sel_hi:[1,0]
	v_pk_mul_f32 v[18:19], v[18:19], v[32:33] op_sel_hi:[1,0]
	v_pk_mul_f32 v[20:21], v[20:21], v[32:33] op_sel_hi:[1,0]
	v_pk_mul_f32 v[22:23], v[22:23], v[32:33] op_sel_hi:[1,0]
	v_pk_mul_f32 v[24:25], v[24:25], v[32:33] op_sel_hi:[1,0]
	v_pk_mul_f32 v[26:27], v[26:27], v[32:33] op_sel_hi:[1,0]
	v_pk_mul_f32 v[28:29], v[28:29], v[32:33] op_sel_hi:[1,0]
	v_pk_mul_f32 v[30:31], v[30:31], v[32:33] op_sel_hi:[1,0]
	v_and_b32_e32 v152, 32, v102
	v_lshrrev_b32_e32 v152, 2, v152
	v_mov_b32_e32 v153, 0
	v_lshl_add_u64 v[200:201], v[34:35], 0, v[130:131]
	v_pk_mul_f32 v[0:1], v[0:1], v[32:33] op_sel_hi:[1,0]
	v_pk_mul_f32 v[2:3], v[2:3], v[32:33] op_sel_hi:[1,0]
	v_pk_mul_f32 v[4:5], v[4:5], v[32:33] op_sel_hi:[1,0]
	v_pk_mul_f32 v[6:7], v[6:7], v[32:33] op_sel_hi:[1,0]
	v_pk_mul_f32 v[8:9], v[8:9], v[32:33] op_sel_hi:[1,0]
	v_pk_mul_f32 v[10:11], v[10:11], v[32:33] op_sel_hi:[1,0]
	v_pk_mul_f32 v[12:13], v[12:13], v[32:33] op_sel_hi:[1,0]
	v_pk_mul_f32 v[14:15], v[14:15], v[32:33] op_sel_hi:[1,0]
	v_cvt_pk_bf16_f32 v104, v16, v17
	v_cvt_pk_bf16_f32 v105, v18, v19
	v_cvt_pk_bf16_f32 v106, v20, v21
	v_cvt_pk_bf16_f32 v107, v22, v23
	v_cvt_pk_bf16_f32 v108, v24, v25
	v_cvt_pk_bf16_f32 v109, v26, v27
	v_cvt_pk_bf16_f32 v110, v28, v29
	v_cvt_pk_bf16_f32 v111, v30, v31
	v_cvt_pk_bf16_f32 v112, v0, v1
	v_cvt_pk_bf16_f32 v113, v2, v3
	v_cvt_pk_bf16_f32 v114, v4, v5
	v_cvt_pk_bf16_f32 v115, v6, v7
	v_cvt_pk_bf16_f32 v116, v8, v9
	v_cvt_pk_bf16_f32 v117, v10, v11
	v_cvt_pk_bf16_f32 v118, v12, v13
	v_cvt_pk_bf16_f32 v119, v14, v15
	v_lshl_add_u64 v[200:201], v[200:201], 0, v[152:153]
	s_lshl_b32 s66, s23, 8
	s_sub_i32 s66, 0x12000, s66
	s_mov_b32 s56, 1
	s_mov_b32 s57, 1
	s_mov_b32 s58, 3
	s_mov_b32 s59, 3
	v_add_u32_e32 v100, v130, v152
	v_lshlrev_b32_e32 v100, 1, v100
	v_add_u32_e32 v100, s66, v100
	v_lshrrev_b32_e32 v32, 12, v84
	v_cmp_gt_u32_e64 s[70:71], 1, v32
	v_cmp_gt_u32_e64 s[94:95], 2, v32
	s_cmp_eq_u64 s[94:95], 0
	v_permlane32_swap_b32_e32 v104, v106
	v_permlane32_swap_b32_e32 v105, v107
	v_permlane32_swap_b32_e32 v108, v110
	v_permlane32_swap_b32_e32 v109, v111
	v_permlane32_swap_b32_e32 v112, v114
	v_permlane32_swap_b32_e32 v113, v115
	v_permlane32_swap_b32_e32 v116, v118
	v_permlane32_swap_b32_e32 v117, v119
	ds_read_b128 v[36:39], v100
	ds_read_b128 v[40:43], v100 offset:16
	ds_read_b128 v[44:47], v100 offset:2048
	ds_read_b128 v[48:51], v100 offset:2064
	ds_read_b128 v[52:55], v100 offset:4096
	ds_read_b128 v[56:59], v100 offset:4112
	ds_read_b128 v[60:63], v100 offset:64
	ds_read_b128 v[64:67], v100 offset:80
	ds_read_b128 v[68:71], v100 offset:2112
	ds_read_b128 v[72:75], v100 offset:2128
	ds_read_b128 v[76:79], v100 offset:4160
	ds_read_b128 v[80:83], v100 offset:4176
	s_waitcnt vmcnt(0)
	v_mov_b32_dpp v0, v182 wave_shr:1 row_mask:0xf bank_mask:0xf
	v_mov_b32_dpp v1, v183 wave_shr:1 row_mask:0xf bank_mask:0xf
	v_mov_b32_dpp v2, v184 wave_shr:1 row_mask:0xf bank_mask:0xf
	v_mov_b32_dpp v3, v185 wave_shr:1 row_mask:0xf bank_mask:0xf
	v_mov_b32_dpp v4, v186 wave_shr:1 row_mask:0xf bank_mask:0xf
	v_mov_b32_dpp v5, v187 wave_shr:1 row_mask:0xf bank_mask:0xf
	v_mov_b32_dpp v6, v188 wave_shr:1 row_mask:0xf bank_mask:0xf
	v_mov_b32_dpp v7, v189 wave_shr:1 row_mask:0xf bank_mask:0xf
	v_mov_b32_dpp v8, v202 wave_shr:1 row_mask:0xf bank_mask:0xf
	v_mov_b32_dpp v9, v203 wave_shr:1 row_mask:0xf bank_mask:0xf
	v_mov_b32_dpp v10, v204 wave_shr:1 row_mask:0xf bank_mask:0xf
	v_mov_b32_dpp v11, v205 wave_shr:1 row_mask:0xf bank_mask:0xf
	v_mov_b32_dpp v12, v206 wave_shr:1 row_mask:0xf bank_mask:0xf
	v_mov_b32_dpp v13, v207 wave_shr:1 row_mask:0xf bank_mask:0xf
	v_mov_b32_dpp v14, v208 wave_shr:1 row_mask:0xf bank_mask:0xf
	v_mov_b32_dpp v15, v209 wave_shr:1 row_mask:0xf bank_mask:0xf
	v_mov_b32_dpp v16, v0 wave_shr:1 row_mask:0xf bank_mask:0xf
	v_mov_b32_dpp v17, v1 wave_shr:1 row_mask:0xf bank_mask:0xf
	v_mov_b32_dpp v18, v2 wave_shr:1 row_mask:0xf bank_mask:0xf
	v_mov_b32_dpp v19, v3 wave_shr:1 row_mask:0xf bank_mask:0xf
	v_mov_b32_dpp v20, v4 wave_shr:1 row_mask:0xf bank_mask:0xf
	v_mov_b32_dpp v21, v5 wave_shr:1 row_mask:0xf bank_mask:0xf
	v_mov_b32_dpp v22, v6 wave_shr:1 row_mask:0xf bank_mask:0xf
	v_mov_b32_dpp v23, v7 wave_shr:1 row_mask:0xf bank_mask:0xf
	v_mov_b32_dpp v24, v8 wave_shr:1 row_mask:0xf bank_mask:0xf
	v_mov_b32_dpp v25, v9 wave_shr:1 row_mask:0xf bank_mask:0xf
	v_mov_b32_dpp v26, v10 wave_shr:1 row_mask:0xf bank_mask:0xf
	v_mov_b32_dpp v27, v11 wave_shr:1 row_mask:0xf bank_mask:0xf
	v_mov_b32_dpp v28, v12 wave_shr:1 row_mask:0xf bank_mask:0xf
	v_mov_b32_dpp v29, v13 wave_shr:1 row_mask:0xf bank_mask:0xf
	v_mov_b32_dpp v30, v14 wave_shr:1 row_mask:0xf bank_mask:0xf
	v_mov_b32_dpp v31, v15 wave_shr:1 row_mask:0xf bank_mask:0xf
	v_mov_b32_dpp v96, v144 wave_shl:1 row_mask:0xf bank_mask:0xf
	v_cndmask_b32_e64 v16, v16, v144, s[58:59]
	s_nop 0
	v_cndmask_b32_e64 v0, v0, v96, s[56:57]
	v_mov_b32_dpp v97, v145 wave_shl:1 row_mask:0xf bank_mask:0xf
	v_cndmask_b32_e64 v17, v17, v145, s[58:59]
	s_nop 0
	v_cndmask_b32_e64 v1, v1, v97, s[56:57]
	v_mov_b32_dpp v96, v146 wave_shl:1 row_mask:0xf bank_mask:0xf
	v_cndmask_b32_e64 v18, v18, v146, s[58:59]
	s_nop 0
	v_cndmask_b32_e64 v2, v2, v96, s[56:57]
	v_mov_b32_dpp v97, v147 wave_shl:1 row_mask:0xf bank_mask:0xf
	v_cndmask_b32_e64 v19, v19, v147, s[58:59]
	s_nop 0
	v_cndmask_b32_e64 v3, v3, v97, s[56:57]
	v_mov_b32_dpp v96, v148 wave_shl:1 row_mask:0xf bank_mask:0xf
	v_cndmask_b32_e64 v20, v20, v148, s[58:59]
	s_nop 0
	v_cndmask_b32_e64 v4, v4, v96, s[56:57]
	v_mov_b32_dpp v97, v149 wave_shl:1 row_mask:0xf bank_mask:0xf
	v_cndmask_b32_e64 v21, v21, v149, s[58:59]
	s_nop 0
	v_cndmask_b32_e64 v5, v5, v97, s[56:57]
	v_mov_b32_dpp v96, v150 wave_shl:1 row_mask:0xf bank_mask:0xf
	v_cndmask_b32_e64 v22, v22, v150, s[58:59]
	s_nop 0
	v_cndmask_b32_e64 v6, v6, v96, s[56:57]
	v_mov_b32_dpp v97, v151 wave_shl:1 row_mask:0xf bank_mask:0xf
	v_cndmask_b32_e64 v23, v23, v151, s[58:59]
	s_nop 0
	v_cndmask_b32_e64 v7, v7, v97, s[56:57]
	v_mov_b32_dpp v96, v192 wave_shl:1 row_mask:0xf bank_mask:0xf
	v_cndmask_b32_e64 v24, v24, v192, s[58:59]
	s_nop 0
	v_cndmask_b32_e64 v8, v8, v96, s[56:57]
	v_mov_b32_dpp v97, v193 wave_shl:1 row_mask:0xf bank_mask:0xf
	v_cndmask_b32_e64 v25, v25, v193, s[58:59]
	s_nop 0
	v_cndmask_b32_e64 v9, v9, v97, s[56:57]
	v_mov_b32_dpp v96, v194 wave_shl:1 row_mask:0xf bank_mask:0xf
	v_cndmask_b32_e64 v26, v26, v194, s[58:59]
	s_nop 0
	v_cndmask_b32_e64 v10, v10, v96, s[56:57]
	v_mov_b32_dpp v97, v195 wave_shl:1 row_mask:0xf bank_mask:0xf
	v_cndmask_b32_e64 v27, v27, v195, s[58:59]
	s_nop 0
	v_cndmask_b32_e64 v11, v11, v97, s[56:57]
	v_mov_b32_dpp v96, v196 wave_shl:1 row_mask:0xf bank_mask:0xf
	v_cndmask_b32_e64 v28, v28, v196, s[58:59]
	s_nop 0
	v_cndmask_b32_e64 v12, v12, v96, s[56:57]
	v_mov_b32_dpp v97, v197 wave_shl:1 row_mask:0xf bank_mask:0xf
	v_cndmask_b32_e64 v29, v29, v197, s[58:59]
	s_nop 0
	v_cndmask_b32_e64 v13, v13, v97, s[56:57]
	v_mov_b32_dpp v96, v198 wave_shl:1 row_mask:0xf bank_mask:0xf
	v_cndmask_b32_e64 v30, v30, v198, s[58:59]
	s_nop 0
	v_cndmask_b32_e64 v14, v14, v96, s[56:57]
	v_mov_b32_dpp v97, v199 wave_shl:1 row_mask:0xf bank_mask:0xf
	v_cndmask_b32_e64 v31, v31, v199, s[58:59]
	s_nop 0
	v_cndmask_b32_e64 v15, v15, v97, s[56:57]
	s_waitcnt lgkmcnt(6)
	s_cbranch_scc1 .Lcf_nomask0
	v_cndmask_b32_e64 v0, v0, 0, s[70:71]
	v_cndmask_b32_e64 v16, v16, 0, s[94:95]
	v_cndmask_b32_e64 v1, v1, 0, s[70:71]
	v_cndmask_b32_e64 v17, v17, 0, s[94:95]
	v_cndmask_b32_e64 v2, v2, 0, s[70:71]
	v_cndmask_b32_e64 v18, v18, 0, s[94:95]
	v_cndmask_b32_e64 v3, v3, 0, s[70:71]
	v_cndmask_b32_e64 v19, v19, 0, s[94:95]
